# early L1 invalidate variant: the XCD-last workgroup invalidates after its TOP arrival (not beside the write-back)
# baseline (speedup 1.0000x reference)
; __device__ __forceinline__ unsigned xb_ld(unsigned* p)              { return __hip_atomic_load(p, __ATOMIC_RELAXED, __HIP_MEMORY_SCOPE_AGENT); }
; __device__ __forceinline__ unsigned xb_add(unsigned* p, unsigned v) { return __hip_atomic_fetch_add(p, v, __ATOMIC_RELAXED, __HIP_MEMORY_SCOPE_AGENT); }
; #define XB_SPIN(cond, bar) do { unsigned _sp = 0; while (cond) { __builtin_amdgcn_s_sleep(1); \
;     if ((++_sp & 255u) == 0u) { if (xb_ld(&(bar)[XB_TMO])) break; if (_sp > XB_SPIN_CAP) { atomicAdd(&(bar)[XB_TMO], 1u); break; } } } } while (0)
; __device__ __forceinline__ void xcd_barrier(const XcdBarrier& b) {
;     ...
;         const unsigned old = xb_add(&bar[XB_XSUB(b.x)], 1u);
;         const unsigned gen = old / nloc;
;         if (old + 1u == (gen + 1u) * nloc) {
;             __builtin_amdgcn_fence(__ATOMIC_RELEASE, "agent");
;             asm volatile("s_waitcnt vmcnt(0)" ::: "memory");
;             const unsigned og = xb_add(&bar[XB_TOP], 1u);
;             const unsigned tg = og / nx;
;             if (og + 1u == (tg + 1u) * nx) xb_add(&bar[XB_TOPGEN], 1u);
;             else XB_SPIN(xb_ld(&bar[XB_TOPGEN]) == tg, bar);
;             __builtin_amdgcn_fence(__ATOMIC_ACQUIRE, "agent");
;             xb_add(&bar[XB_XGEN(b.x)], 1u);
;             asm volatile("s_waitcnt vmcnt(0)" ::: "memory");
.LBB0_100:
	s_mov_b32 s2, 0x27ff0
	s_mov_b32 s3, 0x27ff4
	v_readlane_b32 s12, v254, 41
	v_readlane_b32 s13, v254, 42
	s_waitcnt lgkmcnt(0)
	v_mov_b32_e32 v0, s2
	v_mov_b32_e32 v4, s3
	ds_read_b32 v3, v0
	ds_read_b32 v2, v4
	v_mov_b32_e32 v5, 0
	v_mov_b32_e32 v6, 1
	s_nop 1
	global_atomic_add v6, v5, v6, s[12:13] sc0
	v_readlane_b32 s2, v254, 45
	v_readlane_b32 s3, v254, 46
	s_waitcnt vmcnt(0) lgkmcnt(0)
	v_cvt_f32_u32_e32 v0, v3
	v_sub_u32_e32 v4, 0, v3
	v_rcp_iflag_f32_e32 v0, v0
	s_nop 0
	v_mul_f32_e32 v0, 0x4f7ffffe, v0
	v_cvt_u32_f32_e32 v0, v0
	v_mul_lo_u32 v4, v4, v0
	v_mul_hi_u32 v4, v0, v4
	v_add_u32_e32 v0, v0, v4
	v_mul_hi_u32 v0, v6, v0
	v_mul_lo_u32 v4, v0, v3
	v_sub_u32_e32 v4, v6, v4
	v_add_u32_e32 v7, 1, v0
	v_cmp_ge_u32_e32 vcc, v4, v3
	s_nop 1
	v_cndmask_b32_e32 v0, v0, v7, vcc
	v_sub_u32_e32 v7, v4, v3
	v_cndmask_b32_e32 v4, v4, v7, vcc
	v_add_u32_e32 v7, 1, v0
	v_cmp_ge_u32_e32 vcc, v4, v3
	s_nop 1
	v_cndmask_b32_e32 v0, v0, v7, vcc
	v_add_u32_e32 v7, 1, v0
	v_mul_lo_u32 v4, v7, v3
	v_mul_lo_u32 v7, v7, v2
	v_add_u32_e32 v6, 1, v6
	v_cmp_ne_u32_e32 vcc, v6, v4
	s_mov_b32 s98, 0
	s_cbranch_vccnz .Lxb0_early
	s_nop 0
	buffer_wbl2 sc1
	s_waitcnt vmcnt(0)
	v_mov_b32_e32 v6, 1
	global_atomic_add v5, v6, s[2:3]
	s_branch .Lxb0_early

; __device__ __forceinline__ unsigned xb_ld(unsigned* p)              { return __hip_atomic_load(p, __ATOMIC_RELAXED, __HIP_MEMORY_SCOPE_AGENT); }
; __device__ __forceinline__ unsigned xb_add(unsigned* p, unsigned v) { return __hip_atomic_fetch_add(p, v, __ATOMIC_RELAXED, __HIP_MEMORY_SCOPE_AGENT); }
; #define XB_SPIN(cond, bar) do { unsigned _sp = 0; while (cond) { __builtin_amdgcn_s_sleep(1); \
;     if ((++_sp & 255u) == 0u) { if (xb_ld(&(bar)[XB_TMO])) break; if (_sp > XB_SPIN_CAP) { atomicAdd(&(bar)[XB_TMO], 1u); break; } } } } while (0)
; __device__ __forceinline__ void xcd_barrier(const XcdBarrier& b) {
;     ...
;         const unsigned old = xb_add(&bar[XB_XSUB(b.x)], 1u);
;         const unsigned gen = old / nloc;
;         if (old + 1u == (gen + 1u) * nloc) {
;             __builtin_amdgcn_fence(__ATOMIC_RELEASE, "agent");
;             asm volatile("s_waitcnt vmcnt(0)" ::: "memory");
;             const unsigned og = xb_add(&bar[XB_TOP], 1u);
;             const unsigned tg = og / nx;
;             if (og + 1u == (tg + 1u) * nx) xb_add(&bar[XB_TOPGEN], 1u);
;             else XB_SPIN(xb_ld(&bar[XB_TOPGEN]) == tg, bar);
;             __builtin_amdgcn_fence(__ATOMIC_ACQUIRE, "agent");
;             xb_add(&bar[XB_XGEN(b.x)], 1u);
;             asm volatile("s_waitcnt vmcnt(0)" ::: "memory");
.LBB0_469:
	v_readlane_b32 s2, v254, 59
	v_readlane_b32 s3, v254, 60
	v_readlane_b32 s12, v254, 41
	v_readlane_b32 s13, v254, 42
	s_waitcnt lgkmcnt(0)
	v_mov_b32_e32 v0, s2
	v_mov_b32_e32 v4, s3
	ds_read_b32 v3, v0
	ds_read_b32 v2, v4
	v_mov_b32_e32 v5, 0
	v_mov_b32_e32 v6, 1
	s_nop 1
	global_atomic_add v6, v5, v6, s[12:13] sc0
	v_readlane_b32 s2, v254, 45
	v_readlane_b32 s3, v254, 46
	s_waitcnt vmcnt(0) lgkmcnt(0)
	v_cvt_f32_u32_e32 v0, v3
	v_sub_u32_e32 v4, 0, v3
	v_rcp_iflag_f32_e32 v0, v0
	s_nop 0
	v_mul_f32_e32 v0, 0x4f7ffffe, v0
	v_cvt_u32_f32_e32 v0, v0
	v_mul_lo_u32 v4, v4, v0
	v_mul_hi_u32 v4, v0, v4
	v_add_u32_e32 v0, v0, v4
	v_mul_hi_u32 v0, v6, v0
	v_mul_lo_u32 v4, v0, v3
	v_sub_u32_e32 v4, v6, v4
	v_add_u32_e32 v7, 1, v0
	v_cmp_ge_u32_e32 vcc, v4, v3
	s_nop 1
	v_cndmask_b32_e32 v0, v0, v7, vcc
	v_sub_u32_e32 v7, v4, v3
	v_cndmask_b32_e32 v4, v4, v7, vcc
	v_add_u32_e32 v7, 1, v0
	v_cmp_ge_u32_e32 vcc, v4, v3
	s_nop 1
	v_cndmask_b32_e32 v0, v0, v7, vcc
	v_add_u32_e32 v7, 1, v0
	v_mul_lo_u32 v4, v7, v3
	v_mul_lo_u32 v7, v7, v2
	v_add_u32_e32 v6, 1, v6
	v_cmp_ne_u32_e32 vcc, v6, v4
	s_mov_b32 s98, 0
	s_cbranch_vccnz .Lxb1_early
	s_nop 0
	buffer_wbl2 sc1
	s_waitcnt vmcnt(0)
	v_mov_b32_e32 v6, 1
	global_atomic_add v5, v6, s[2:3]
	s_branch .Lxb1_early
